# layer-1 weight conversion split: w_in/w_out in the idle 5th round of layer-0 MLP-up, w_mlp1 beside layer-0 MLP-down K-split pieces, only w_mlp2 left at layer end
# baseline (speedup 1.0000x reference)
.LBB0_15:
	s_waitcnt lgkmcnt(0)
	v_writelane_b32 v253, s36, 0
	v_writelane_b32 v253, s37, 1
	v_writelane_b32 v253, s38, 2
	v_writelane_b32 v253, s39, 3
	v_writelane_b32 v253, s40, 4
	v_writelane_b32 v253, s41, 5
	v_writelane_b32 v253, s42, 6
	v_writelane_b32 v253, s43, 7
	v_writelane_b32 v253, s44, 8
	v_writelane_b32 v253, s45, 9
	v_writelane_b32 v253, s46, 10
	v_writelane_b32 v253, s47, 11
	v_writelane_b32 v253, s48, 12
	v_writelane_b32 v253, s49, 13
	v_writelane_b32 v253, s50, 14
	v_writelane_b32 v253, s51, 15
	v_writelane_b32 v253, s52, 16
	v_writelane_b32 v253, s53, 17
	v_writelane_b32 v253, s54, 18
	v_writelane_b32 v253, s55, 19
	v_writelane_b32 v253, s56, 20
	v_writelane_b32 v253, s57, 21
	v_writelane_b32 v253, s58, 22
	v_writelane_b32 v253, s59, 23
	v_writelane_b32 v253, s60, 24
	v_writelane_b32 v253, s61, 25
	v_writelane_b32 v253, s62, 26
	v_writelane_b32 v253, s63, 27
	v_writelane_b32 v253, s64, 28
	v_writelane_b32 v253, s65, 29
	v_writelane_b32 v253, s66, 30
	v_writelane_b32 v253, s67, 31
	s_mov_b64 s[36:37], exec
	v_writelane_b32 v253, s36, 32
	v_writelane_b32 v253, s37, 33
	v_writelane_b32 v253, vcc_lo, 34
	v_writelane_b32 v253, vcc_hi, 35
	s_mov_b64 exec, -1
	s_load_dwordx2 s[36:37], s[0:1], 0x50
	s_load_dwordx2 s[38:39], s[0:1], 0xe8
	s_load_dwordx4 s[40:43], s[0:1], 0xf0
	s_load_dwordx2 s[44:45], s[0:1], 0x108
	s_waitcnt lgkmcnt(0)
	v_and_b32_e32 v200, 15, v156
	v_lshlrev_b32_e32 v200, 4, v200
	v_lshrrev_b32_e32 v201, 4, v156
	v_mul_u32_u24_e32 v202, 0x110, v201
	v_add_u32_e32 v202, v202, v200
	v_lshrrev_b32_e32 v203, 3, v156
	v_and_b32_e32 v204, 7, v156
	v_lshlrev_b32_e32 v204, 4, v204
	v_and_b32_e32 v205, 7, v156
	v_mul_u32_u24_e32 v205, 0x880, v205
	v_lshl_add_u32 v205, v203, 2, v205
	v_add_u32_e32 v206, 0x400, v205
	s_sub_u32 s46, s92, 0x0
	s_add_u32 s46, s46, 0x0
	s_cmp_ge_u32 s46, 0xb70
	s_cbranch_scc1 .LcvA_done
	s_mov_b32 s47, 0
	v_add_u32_e32 v240, 0x4400, v205
	v_add_u32_e32 v241, 0x4400, v206
	s_mov_b32 s62, s46
	s_cmp_lt_u32 s62, 624
	s_cbranch_scc1 .LcvA_ld1_win
	s_cmp_lt_u32 s62, 880
	s_cbranch_scc1 .LcvA_ld1_wout
	s_cmp_lt_u32 s62, 1904
	s_cbranch_scc1 .LcvA_ld1_w1

.LBB0_1307:
	s_cmp_lg_u32 s93, 0
	s_cbranch_scc1 .LcvC_skip
	s_cmp_lt_u32 s92, 0x20
	s_cbranch_scc1 .LcvC_skip
	s_waitcnt lgkmcnt(0)
	v_writelane_b32 v253, s36, 0
	v_writelane_b32 v253, s37, 1
	v_writelane_b32 v253, s38, 2
	v_writelane_b32 v253, s39, 3
	v_writelane_b32 v253, s40, 4
	v_writelane_b32 v253, s41, 5
	v_writelane_b32 v253, s42, 6
	v_writelane_b32 v253, s43, 7
	v_writelane_b32 v253, s44, 8
	v_writelane_b32 v253, s45, 9
	v_writelane_b32 v253, s46, 10
	v_writelane_b32 v253, s47, 11
	v_writelane_b32 v253, s48, 12
	v_writelane_b32 v253, s49, 13
	v_writelane_b32 v253, s50, 14
	v_writelane_b32 v253, s51, 15
	v_writelane_b32 v253, s52, 16
	v_writelane_b32 v253, s53, 17
	v_writelane_b32 v253, s54, 18
	v_writelane_b32 v253, s55, 19
	v_writelane_b32 v253, s56, 20
	v_writelane_b32 v253, s57, 21
	v_writelane_b32 v253, s58, 22
	v_writelane_b32 v253, s59, 23
	v_writelane_b32 v253, s60, 24
	v_writelane_b32 v253, s61, 25
	v_writelane_b32 v253, s62, 26
	v_writelane_b32 v253, s63, 27
	v_writelane_b32 v253, s64, 28
	v_writelane_b32 v253, s65, 29
	v_writelane_b32 v253, s66, 30
	v_writelane_b32 v253, s67, 31
	s_mov_b64 s[36:37], exec
	v_writelane_b32 v253, s36, 32
	v_writelane_b32 v253, s37, 33
	v_writelane_b32 v253, vcc_lo, 34
	v_writelane_b32 v253, vcc_hi, 35
	s_mov_b64 exec, -1
	s_load_dwordx2 s[36:37], s[0:1], 0x50
	s_load_dwordx2 s[38:39], s[0:1], 0xe8
	s_load_dwordx4 s[40:43], s[0:1], 0xf0
	s_load_dwordx2 s[44:45], s[0:1], 0x108
	s_waitcnt lgkmcnt(0)
	s_add_u32 s36, s36, 0x9c0000
	s_addc_u32 s37, s37, 0
	s_add_u32 s38, s38, 0x400000
	s_addc_u32 s39, s39, 0
	s_add_u32 s40, s40, 0x1000000
	s_addc_u32 s41, s41, 0
	s_add_u32 s42, s42, 0x1000000
	s_addc_u32 s43, s43, 0
	v_and_b32_e32 v200, 15, v156
	v_lshlrev_b32_e32 v200, 4, v200
	v_lshrrev_b32_e32 v201, 4, v156
	v_mul_u32_u24_e32 v202, 0x110, v201
	v_add_u32_e32 v202, v202, v200
	v_lshrrev_b32_e32 v203, 3, v156
	v_and_b32_e32 v204, 7, v156
	v_lshlrev_b32_e32 v204, 4, v204
	v_and_b32_e32 v205, 7, v156
	v_mul_u32_u24_e32 v205, 0x880, v205
	v_lshl_add_u32 v205, v203, 2, v205
	v_add_u32_e32 v206, 0x400, v205
	s_sub_u32 s46, s92, 0x20
	s_add_u32 s46, s46, 0x0
	s_cmp_ge_u32 s46, 0x370
	s_cbranch_scc1 .LcvC_done
	s_mov_b32 s47, 0
	v_add_u32_e32 v240, 0x4400, v205
	v_add_u32_e32 v241, 0x4400, v206
	s_mov_b32 s62, s46
	s_cmp_lt_u32 s62, 624
	s_cbranch_scc1 .LcvC_ld1_win
	s_cmp_lt_u32 s62, 880
	s_cbranch_scc1 .LcvC_ld1_wout
	s_cmp_lt_u32 s62, 1904
	s_cbranch_scc1 .LcvC_ld1_w1

.LcvC_loop:
	s_add_u32 s62, s46, 0xe0
	s_cmp_ge_u32 s62, 0x370
	s_cbranch_scc1 .LcvC_nonext0
	s_cmp_lt_u32 s62, 624
	s_cbranch_scc1 .LcvC_ld2_win
	s_cmp_lt_u32 s62, 880
	s_cbranch_scc1 .LcvC_ld2_wout
	s_cmp_lt_u32 s62, 1904
	s_cbranch_scc1 .LcvC_ld2_w1

.LcvC_st0_end:
	s_lshl_b32 s55, s55, 6
	s_lshl_b32 s59, s59, 6
	s_mul_i32 s58, s59, s50
	s_lshl_b32 s61, s55, 2
	s_add_u32 s58, s58, s61
	s_add_u32 s48, s48, s58
	s_addc_u32 s49, s49, 0
	s_lshl_b32 s51, s50, 5
	s_lshl_b32 s61, s59, 1
	s_add_u32 s60, s60, s61
	s_add_u32 s52, s44, s60
	s_addc_u32 s53, s45, 0
	v_add_u32_e32 v236, s55, v203
	v_mov_b32_e32 v237, 0x60
	v_mov_b32_e32 v238, 0xe0
	v_cmp_le_u32_e32 vcc, s56, v236
	s_nop 1
	v_cndmask_b32_e32 v237, 0, v237, vcc
	v_cmp_le_u32_e32 vcc, s57, v236
	s_nop 1
	v_cndmask_b32_e32 v238, 0, v238, vcc
	v_add3_u32 v236, v236, v237, v238
	v_mad_u32_u24 v236, v236, s54, v204
	s_waitcnt lgkmcnt(0)
	v_cvt_pk_bf16_f32 v232, v224, v225
	v_cvt_pk_bf16_f32 v233, v226, v227
	v_cvt_pk_bf16_f32 v234, v228, v229
	v_cvt_pk_bf16_f32 v235, v230, v231
	global_store_dwordx4 v236, v[232:235], s[52:53]
	s_mov_b32 s47, 1
	s_add_u32 s46, s46, 0xe0
	s_cmp_ge_u32 s46, 0x370
	s_cbranch_scc1 .LcvC_done
	s_add_u32 s62, s46, 0xe0
	s_cmp_ge_u32 s62, 0x370
	s_cbranch_scc1 .LcvC_nonext1
	s_cmp_lt_u32 s62, 624
	s_cbranch_scc1 .LcvC_ld3_win
	s_cmp_lt_u32 s62, 880
	s_cbranch_scc1 .LcvC_ld3_wout
	s_cmp_lt_u32 s62, 1904
	s_cbranch_scc1 .LcvC_ld3_w1

.LcvC_st1_end:
	s_lshl_b32 s55, s55, 6
	s_lshl_b32 s59, s59, 6
	s_mul_i32 s58, s59, s50
	s_lshl_b32 s61, s55, 2
	s_add_u32 s58, s58, s61
	s_add_u32 s48, s48, s58
	s_addc_u32 s49, s49, 0
	s_lshl_b32 s51, s50, 5
	s_lshl_b32 s61, s59, 1
	s_add_u32 s60, s60, s61
	s_add_u32 s52, s44, s60
	s_addc_u32 s53, s45, 0
	v_add_u32_e32 v236, s55, v203
	v_mov_b32_e32 v237, 0x60
	v_mov_b32_e32 v238, 0xe0
	v_cmp_le_u32_e32 vcc, s56, v236
	s_nop 1
	v_cndmask_b32_e32 v237, 0, v237, vcc
	v_cmp_le_u32_e32 vcc, s57, v236
	s_nop 1
	v_cndmask_b32_e32 v238, 0, v238, vcc
	v_add3_u32 v236, v236, v237, v238
	v_mad_u32_u24 v236, v236, s54, v204
	s_waitcnt lgkmcnt(0)
	v_cvt_pk_bf16_f32 v232, v224, v225
	v_cvt_pk_bf16_f32 v233, v226, v227
	v_cvt_pk_bf16_f32 v234, v228, v229
	v_cvt_pk_bf16_f32 v235, v230, v231
	global_store_dwordx4 v236, v[232:235], s[52:53]
	s_mov_b32 s47, 1
	s_add_u32 s46, s46, 0xe0
	s_cmp_ge_u32 s46, 0x370
	s_cbranch_scc1 .LcvC_done
	s_branch .LcvC_loop
.LcvC_done:
	s_waitcnt vmcnt(0) lgkmcnt(0)
	s_barrier
	v_readlane_b32 vcc_lo, v253, 34
	v_readlane_b32 vcc_hi, v253, 35
	v_readlane_b32 s36, v253, 32
	v_readlane_b32 s37, v253, 33
	s_nop 3
	s_mov_b64 exec, s[36:37]
	v_readlane_b32 s36, v253, 0
	v_readlane_b32 s37, v253, 1
	v_readlane_b32 s38, v253, 2
	v_readlane_b32 s39, v253, 3
	v_readlane_b32 s40, v253, 4
	v_readlane_b32 s41, v253, 5
	v_readlane_b32 s42, v253, 6
	v_readlane_b32 s43, v253, 7
	v_readlane_b32 s44, v253, 8
	v_readlane_b32 s45, v253, 9
	v_readlane_b32 s46, v253, 10
	v_readlane_b32 s47, v253, 11
	v_readlane_b32 s48, v253, 12
	v_readlane_b32 s49, v253, 13
	v_readlane_b32 s50, v253, 14
	v_readlane_b32 s51, v253, 15
	v_readlane_b32 s52, v253, 16
	v_readlane_b32 s53, v253, 17
	v_readlane_b32 s54, v253, 18
	v_readlane_b32 s55, v253, 19
	v_readlane_b32 s56, v253, 20
	v_readlane_b32 s57, v253, 21
	v_readlane_b32 s58, v253, 22
	v_readlane_b32 s59, v253, 23
	v_readlane_b32 s60, v253, 24
	v_readlane_b32 s61, v253, 25
	v_readlane_b32 s62, v253, 26
	v_readlane_b32 s63, v253, 27
	v_readlane_b32 s64, v253, 28
	v_readlane_b32 s65, v253, 29
	v_readlane_b32 s66, v253, 30
	v_readlane_b32 s67, v253, 31
	s_nop 3
.LcvC_skip:
	s_getreg_b32 s8, hwreg(HW_REG_XCC_ID, 0, 4)
	s_waitcnt vmcnt(0)
	v_mov_b32_e32 v0, v156
	s_waitcnt vmcnt(0)
	s_barrier
	s_nop 0
	v_cmp_eq_u32_e32 vcc, 0, v0
	s_and_saveexec_b64 s[4:5], vcc
	s_cbranch_execz .LBB0_1359
	v_readlane_b32 s9, v254, 22
	s_load_dwordx2 s[6:7], s[0:1], 0x108
	s_waitcnt vmcnt(0) expcnt(0) lgkmcnt(0)
	v_mov_b32_e32 v0, s9
	ds_read_b32 v3, v0
	v_readlane_b32 s9, v254, 23
	s_and_b32 s37, s8, 15
	s_waitcnt lgkmcnt(0)
	v_cmp_ne_u32_e32 vcc, 0, v3
	v_mov_b32_e32 v0, s9
	ds_read_b32 v2, v0
	s_cbranch_vccnz .LBB0_1323
	s_add_u32 s8, s6, 0x1000
	s_addc_u32 s9, s7, 0
	s_add_u32 s10, s6, 0x1100
	s_addc_u32 s11, s7, 0
	s_add_u32 s12, s6, 0x1200
	s_addc_u32 s13, s7, 0
	s_add_u32 s14, s6, 0x1300
	s_addc_u32 s15, s7, 0
	s_mov_b32 s42, 1
	s_branch .LBB0_1311

.LBB0_1392:
	s_cmp_lg_u32 s93, 0
	s_cbranch_scc1 .LcvD_skip
	s_cmp_lt_u32 s92, 0x40
	s_cbranch_scc1 .LcvD_skip
	s_waitcnt lgkmcnt(0)
	v_writelane_b32 v253, s36, 0
	v_writelane_b32 v253, s37, 1
	v_writelane_b32 v253, s38, 2
	v_writelane_b32 v253, s39, 3
	v_writelane_b32 v253, s40, 4
	v_writelane_b32 v253, s41, 5
	v_writelane_b32 v253, s42, 6
	v_writelane_b32 v253, s43, 7
	v_writelane_b32 v253, s44, 8
	v_writelane_b32 v253, s45, 9
	v_writelane_b32 v253, s46, 10
	v_writelane_b32 v253, s47, 11
	v_writelane_b32 v253, s48, 12
	v_writelane_b32 v253, s49, 13
	v_writelane_b32 v253, s50, 14
	v_writelane_b32 v253, s51, 15
	v_writelane_b32 v253, s52, 16
	v_writelane_b32 v253, s53, 17
	v_writelane_b32 v253, s54, 18
	v_writelane_b32 v253, s55, 19
	v_writelane_b32 v253, s56, 20
	v_writelane_b32 v253, s57, 21
	v_writelane_b32 v253, s58, 22
	v_writelane_b32 v253, s59, 23
	v_writelane_b32 v253, s60, 24
	v_writelane_b32 v253, s61, 25
	v_writelane_b32 v253, s62, 26
	v_writelane_b32 v253, s63, 27
	v_writelane_b32 v253, s64, 28
	v_writelane_b32 v253, s65, 29
	v_writelane_b32 v253, s66, 30
	v_writelane_b32 v253, s67, 31
	s_mov_b64 s[36:37], exec
	v_writelane_b32 v253, s36, 32
	v_writelane_b32 v253, s37, 33
	v_writelane_b32 v253, vcc_lo, 34
	v_writelane_b32 v253, vcc_hi, 35
	s_mov_b64 exec, -1
	s_load_dwordx2 s[36:37], s[0:1], 0x50
	s_load_dwordx2 s[38:39], s[0:1], 0xe8
	s_load_dwordx4 s[40:43], s[0:1], 0xf0
	s_load_dwordx2 s[44:45], s[0:1], 0x108
	s_waitcnt lgkmcnt(0)
	s_add_u32 s36, s36, 0x9c0000
	s_addc_u32 s37, s37, 0
	s_add_u32 s38, s38, 0x400000
	s_addc_u32 s39, s39, 0
	s_add_u32 s40, s40, 0x1000000
	s_addc_u32 s41, s41, 0
	s_add_u32 s42, s42, 0x1000000
	s_addc_u32 s43, s43, 0
	v_and_b32_e32 v200, 15, v156
	v_lshlrev_b32_e32 v200, 4, v200
	v_lshrrev_b32_e32 v201, 4, v156
	v_mul_u32_u24_e32 v202, 0x110, v201
	v_add_u32_e32 v202, v202, v200
	v_lshrrev_b32_e32 v203, 3, v156
	v_and_b32_e32 v204, 7, v156
	v_lshlrev_b32_e32 v204, 4, v204
	v_and_b32_e32 v205, 7, v156
	v_mul_u32_u24_e32 v205, 0x880, v205
	v_lshl_add_u32 v205, v203, 2, v205
	v_add_u32_e32 v206, 0x400, v205
	s_sub_u32 s46, s92, 0x40
	s_add_u32 s46, s46, 0x370
	s_cmp_ge_u32 s46, 0x770
	s_cbranch_scc1 .LcvD_done
	s_mov_b32 s47, 0
	v_add_u32_e32 v240, 0x4400, v205
	v_add_u32_e32 v241, 0x4400, v206
	s_mov_b32 s62, s46
	s_cmp_lt_u32 s62, 624
	s_cbranch_scc1 .LcvD_ld1_win
	s_cmp_lt_u32 s62, 880
	s_cbranch_scc1 .LcvD_ld1_wout
	s_cmp_lt_u32 s62, 1904
	s_cbranch_scc1 .LcvD_ld1_w1

.LcvD_loop:
	s_add_u32 s62, s46, 0xc0
	s_cmp_ge_u32 s62, 0x770
	s_cbranch_scc1 .LcvD_nonext0
	s_cmp_lt_u32 s62, 624
	s_cbranch_scc1 .LcvD_ld2_win
	s_cmp_lt_u32 s62, 880
	s_cbranch_scc1 .LcvD_ld2_wout
	s_cmp_lt_u32 s62, 1904
	s_cbranch_scc1 .LcvD_ld2_w1

.LcvD_st0_end:
	s_lshl_b32 s55, s55, 6
	s_lshl_b32 s59, s59, 6
	s_mul_i32 s58, s59, s50
	s_lshl_b32 s61, s55, 2
	s_add_u32 s58, s58, s61
	s_add_u32 s48, s48, s58
	s_addc_u32 s49, s49, 0
	s_lshl_b32 s51, s50, 5
	s_lshl_b32 s61, s59, 1
	s_add_u32 s60, s60, s61
	s_add_u32 s52, s44, s60
	s_addc_u32 s53, s45, 0
	v_add_u32_e32 v236, s55, v203
	v_mov_b32_e32 v237, 0x60
	v_mov_b32_e32 v238, 0xe0
	v_cmp_le_u32_e32 vcc, s56, v236
	s_nop 1
	v_cndmask_b32_e32 v237, 0, v237, vcc
	v_cmp_le_u32_e32 vcc, s57, v236
	s_nop 1
	v_cndmask_b32_e32 v238, 0, v238, vcc
	v_add3_u32 v236, v236, v237, v238
	v_mad_u32_u24 v236, v236, s54, v204
	s_waitcnt lgkmcnt(0)
	v_cvt_pk_bf16_f32 v232, v224, v225
	v_cvt_pk_bf16_f32 v233, v226, v227
	v_cvt_pk_bf16_f32 v234, v228, v229
	v_cvt_pk_bf16_f32 v235, v230, v231
	global_store_dwordx4 v236, v[232:235], s[52:53]
	s_mov_b32 s47, 1
	s_add_u32 s46, s46, 0xc0
	s_cmp_ge_u32 s46, 0x770
	s_cbranch_scc1 .LcvD_done
	s_add_u32 s62, s46, 0xc0
	s_cmp_ge_u32 s62, 0x770
	s_cbranch_scc1 .LcvD_nonext1
	s_cmp_lt_u32 s62, 624
	s_cbranch_scc1 .LcvD_ld3_win
	s_cmp_lt_u32 s62, 880
	s_cbranch_scc1 .LcvD_ld3_wout
	s_cmp_lt_u32 s62, 1904
	s_cbranch_scc1 .LcvD_ld3_w1

.LcvD_st1_end:
	s_lshl_b32 s55, s55, 6
	s_lshl_b32 s59, s59, 6
	s_mul_i32 s58, s59, s50
	s_lshl_b32 s61, s55, 2
	s_add_u32 s58, s58, s61
	s_add_u32 s48, s48, s58
	s_addc_u32 s49, s49, 0
	s_lshl_b32 s51, s50, 5
	s_lshl_b32 s61, s59, 1
	s_add_u32 s60, s60, s61
	s_add_u32 s52, s44, s60
	s_addc_u32 s53, s45, 0
	v_add_u32_e32 v236, s55, v203
	v_mov_b32_e32 v237, 0x60
	v_mov_b32_e32 v238, 0xe0
	v_cmp_le_u32_e32 vcc, s56, v236
	s_nop 1
	v_cndmask_b32_e32 v237, 0, v237, vcc
	v_cmp_le_u32_e32 vcc, s57, v236
	s_nop 1
	v_cndmask_b32_e32 v238, 0, v238, vcc
	v_add3_u32 v236, v236, v237, v238
	v_mad_u32_u24 v236, v236, s54, v204
	s_waitcnt lgkmcnt(0)
	v_cvt_pk_bf16_f32 v232, v224, v225
	v_cvt_pk_bf16_f32 v233, v226, v227
	v_cvt_pk_bf16_f32 v234, v228, v229
	v_cvt_pk_bf16_f32 v235, v230, v231
	global_store_dwordx4 v236, v[232:235], s[52:53]
	s_mov_b32 s47, 1
	s_add_u32 s46, s46, 0xc0
	s_cmp_ge_u32 s46, 0x770
	s_cbranch_scc1 .LcvD_done
	s_branch .LcvD_loop
.LcvD_done:
	s_waitcnt vmcnt(0) lgkmcnt(0)
	s_barrier
	v_readlane_b32 vcc_lo, v253, 34
	v_readlane_b32 vcc_hi, v253, 35
	v_readlane_b32 s36, v253, 32
	v_readlane_b32 s37, v253, 33
	s_nop 3
	s_mov_b64 exec, s[36:37]
	v_readlane_b32 s36, v253, 0
	v_readlane_b32 s37, v253, 1
	v_readlane_b32 s38, v253, 2
	v_readlane_b32 s39, v253, 3
	v_readlane_b32 s40, v253, 4
	v_readlane_b32 s41, v253, 5
	v_readlane_b32 s42, v253, 6
	v_readlane_b32 s43, v253, 7
	v_readlane_b32 s44, v253, 8
	v_readlane_b32 s45, v253, 9
	v_readlane_b32 s46, v253, 10
	v_readlane_b32 s47, v253, 11
	v_readlane_b32 s48, v253, 12
	v_readlane_b32 s49, v253, 13
	v_readlane_b32 s50, v253, 14
	v_readlane_b32 s51, v253, 15
	v_readlane_b32 s52, v253, 16
	v_readlane_b32 s53, v253, 17
	v_readlane_b32 s54, v253, 18
	v_readlane_b32 s55, v253, 19
	v_readlane_b32 s56, v253, 20
	v_readlane_b32 s57, v253, 21
	v_readlane_b32 s58, v253, 22
	v_readlane_b32 s59, v253, 23
	v_readlane_b32 s60, v253, 24
	v_readlane_b32 s61, v253, 25
	v_readlane_b32 s62, v253, 26
	v_readlane_b32 s63, v253, 27
	v_readlane_b32 s64, v253, 28
	v_readlane_b32 s65, v253, 29
	v_readlane_b32 s66, v253, 30
	v_readlane_b32 s67, v253, 31
	s_nop 3
.LcvD_skip:
	s_getreg_b32 s8, hwreg(HW_REG_XCC_ID, 0, 4)
	s_waitcnt vmcnt(0)
	v_mov_b32_e32 v0, v156
	s_waitcnt vmcnt(0)
	s_barrier
	s_nop 0
	v_cmp_eq_u32_e32 vcc, 0, v0
	s_and_saveexec_b64 s[4:5], vcc
	s_cbranch_execz .LBB0_1444
	v_readlane_b32 s9, v254, 22
	s_load_dwordx2 s[6:7], s[0:1], 0x108
	s_waitcnt vmcnt(0) expcnt(0) lgkmcnt(0)
	v_mov_b32_e32 v0, s9
	ds_read_b32 v3, v0
	v_readlane_b32 s9, v254, 23
	s_and_b32 s37, s8, 15
	s_waitcnt lgkmcnt(0)
	v_cmp_ne_u32_e32 vcc, 0, v3
	v_mov_b32_e32 v0, s9
	ds_read_b32 v2, v0
	s_cbranch_vccnz .LBB0_1408
	s_add_u32 s8, s6, 0x1000
	s_addc_u32 s9, s7, 0
	s_add_u32 s10, s6, 0x1100
	s_addc_u32 s11, s7, 0
	s_add_u32 s12, s6, 0x1200
	s_addc_u32 s13, s7, 0
	s_add_u32 s14, s6, 0x1300
	s_addc_u32 s15, s7, 0
	s_mov_b32 s42, 1
	s_branch .LBB0_1396

.LBB0_1444:
	s_or_b64 exec, exec, s[4:5]
	s_waitcnt lgkmcnt(0)
	s_barrier
	s_load_dwordx2 s[50:51], s[0:1], 0x30
	s_load_dwordx2 s[68:69], s[0:1], 0x48
	s_load_dwordx2 s[26:27], s[0:1], 0x108
	s_load_dwordx8 s[4:11], s[0:1], 0xe8
	s_and_b64 vcc, exec, s[2:3]
	s_cbranch_vccnz .LBB0_1452
	s_waitcnt lgkmcnt(0)
	v_writelane_b32 v253, s36, 0
	v_writelane_b32 v253, s37, 1
	v_writelane_b32 v253, s38, 2
	v_writelane_b32 v253, s39, 3
	v_writelane_b32 v253, s40, 4
	v_writelane_b32 v253, s41, 5
	v_writelane_b32 v253, s42, 6
	v_writelane_b32 v253, s43, 7
	v_writelane_b32 v253, s44, 8
	v_writelane_b32 v253, s45, 9
	v_writelane_b32 v253, s46, 10
	v_writelane_b32 v253, s47, 11
	v_writelane_b32 v253, s48, 12
	v_writelane_b32 v253, s49, 13
	v_writelane_b32 v253, s50, 14
	v_writelane_b32 v253, s51, 15
	v_writelane_b32 v253, s52, 16
	v_writelane_b32 v253, s53, 17
	v_writelane_b32 v253, s54, 18
	v_writelane_b32 v253, s55, 19
	v_writelane_b32 v253, s56, 20
	v_writelane_b32 v253, s57, 21
	v_writelane_b32 v253, s58, 22
	v_writelane_b32 v253, s59, 23
	v_writelane_b32 v253, s60, 24
	v_writelane_b32 v253, s61, 25
	v_writelane_b32 v253, s62, 26
	v_writelane_b32 v253, s63, 27
	v_writelane_b32 v253, s64, 28
	v_writelane_b32 v253, s65, 29
	v_writelane_b32 v253, s66, 30
	v_writelane_b32 v253, s67, 31
	s_mov_b64 s[36:37], exec
	v_writelane_b32 v253, s36, 32
	v_writelane_b32 v253, s37, 33
	v_writelane_b32 v253, vcc_lo, 34
	v_writelane_b32 v253, vcc_hi, 35
	s_mov_b64 exec, -1
	s_load_dwordx2 s[36:37], s[0:1], 0x50
	s_load_dwordx2 s[38:39], s[0:1], 0xe8
	s_load_dwordx4 s[40:43], s[0:1], 0xf0
	s_load_dwordx2 s[44:45], s[0:1], 0x108
	s_waitcnt lgkmcnt(0)
	s_add_u32 s36, s36, 0x9c0000
	s_addc_u32 s37, s37, 0
	s_add_u32 s38, s38, 0x400000
	s_addc_u32 s39, s39, 0
	s_add_u32 s40, s40, 0x1000000
	s_addc_u32 s41, s41, 0
	s_add_u32 s42, s42, 0x1000000
	s_addc_u32 s43, s43, 0
	v_and_b32_e32 v200, 15, v156
	v_lshlrev_b32_e32 v200, 4, v200
	v_lshrrev_b32_e32 v201, 4, v156
	v_mul_u32_u24_e32 v202, 0x110, v201
	v_add_u32_e32 v202, v202, v200
	v_lshrrev_b32_e32 v203, 3, v156
	v_and_b32_e32 v204, 7, v156
	v_lshlrev_b32_e32 v204, 4, v204
	v_and_b32_e32 v205, 7, v156
	v_mul_u32_u24_e32 v205, 0x880, v205
	v_lshl_add_u32 v205, v203, 2, v205
	v_add_u32_e32 v206, 0x400, v205
	s_sub_u32 s46, s92, 0x0
	s_add_u32 s46, s46, 0x770
	s_cmp_ge_u32 s46, 0xb70
	s_cbranch_scc1 .LcvB_done
	s_mov_b32 s47, 0
	v_add_u32_e32 v240, 0x4400, v205
	v_add_u32_e32 v241, 0x4400, v206
	s_mov_b32 s62, s46
	s_cmp_lt_u32 s62, 624
	s_cbranch_scc1 .LcvB_ld1_win
	s_cmp_lt_u32 s62, 880
	s_cbranch_scc1 .LcvB_ld1_wout
	s_cmp_lt_u32 s62, 1904
	s_cbranch_scc1 .LcvB_ld1_w1
